# SWA: 32-key halves that lie entirely outside the wave's window (one in six) are skipped, they contribute exactly zero; stacked on hazard-window fill + full stack
# speedup vs baseline: 1.0032x; 1.0027x over previous
.LBB0_1290:
	v_readfirstlane_b32 s99, v173
	s_lshl_b32 s100, s37, 6
	s_add_i32 s100, s100, s50
	s_sub_i32 s100, s100, s99
	s_cmp_gt_i32 s100, 31
	s_cbranch_scc1 .Lswa_skiphalf
	s_cmp_lt_i32 s100, 0xffffff62
	s_cbranch_scc0 .Lswa_dohalf
.Lswa_skiphalf:
	s_xor_b64 s[82:83], s[84:85], -1
	s_mov_b32 s50, 32
	s_mov_b64 s[84:85], 0
	s_and_b64 vcc, exec, s[82:83]
	s_cbranch_vccnz .LBB0_1292
	s_branch .LBB0_1290
